# attention: waves 4-7 run the tile loop rotated by half a tile (PV of previous tile first) over 3 LDS buffers so matrix and exp phases of SIMD partners overlap
# speedup vs baseline: 1.0685x; 1.0101x over previous
; #define LAS __attribute__((address_space(3)))
; __device__ __forceinline__ unsigned cvtpk(float lo, float hi) { f32x2_t v = {lo, hi}; bf16x2_t b = __builtin_convertvector(v, bf16x2_t); return __builtin_bit_cast(unsigned, b); }
; __device__ __forceinline__ f32x4 mfma16(bf16x8 a, bf16x8 b, f32x4 c) { return __builtin_amdgcn_mfma_f32_16x16x32_bf16(a, b, c, 0, 0, 0); }
; __device__ __forceinline__ u32x2 tr_rd(const LAS bf16_t* p) { return __builtin_bit_cast(u32x2, __builtin_amdgcn_ds_read_tr16_b64_v4i16((LAS v4i16_t*)p)); }
; __device__ __forceinline__ void attn_unit(LAS unsigned char* lds, const bf16_t* Q, const bf16_t* KV, const bf16_t* KR, bf16_t* MIX, size_t qrow0, size_t krow0, int ntiles, int h, const int tid) {
;     ...
; #pragma unroll
;     for (int s2 = 0; s2 < 2; ++s2) {
;       bf16x8 pf[2];
; #pragma unroll
;       for (int qb = 0; qb < 2; ++qb) { u32x4 w; w.x = cvtpk(s[2 * s2][qb][0], s[2 * s2][qb][1]); w.y = cvtpk(s[2 * s2][qb][2], s[2 * s2][qb][3]);
;         w.z = cvtpk(s[2 * s2 + 1][qb][0], s[2 * s2 + 1][qb][1]); w.w = cvtpk(s[2 * s2 + 1][qb][2], s[2 * s2 + 1][qb][3]); pf[qb] = __builtin_bit_cast(bf16x8, w);
;         lacc[qb] = mfma16(ones, pf[qb], lacc[qb]); }
;       const LAS bf16_t* vb = Vs + (32 * s2 + 4 * quad + tq) * AT_VSTR + 4 * tp;
; #pragma unroll
;       for (int eb = 0; eb < 4; ++eb) {
;         const u32x2 lo = tr_rd(vb + 16 * eb), hi = tr_rd(vb + 16 * AT_VSTR + 16 * eb);
;         const u32x4 vv = (u32x4){lo.x, lo.y, hi.x, hi.y}; const bf16x8 vf = __builtin_bit_cast(bf16x8, vv);
; #pragma unroll
;         for (int qb = 0; qb < 2; ++qb) o[qb][eb] = mfma16(vf, pf[qb], o[qb][eb]);
;       }
;     }
;     if (more) attn_stage(lds + ((t + 1) & 1) * AT_BUF, tid, rk, rv, rr);
;     __syncthreads();
;   }
; #pragma unroll
;   for (int qb = 0; qb < 2; ++qb) {
;     const float inv = 1.f / lacc[qb][0];
;     bf16_t* op = MIX + (qrow0 + wid * 32 + qb * 16 + c16) * 1024 + h * 64 + quad * 4;
; #pragma unroll
;     for (int eb = 0; eb < 4; ++eb) { u32x2 w; w.x = cvtpk(o[qb][eb][0] * inv, o[qb][eb][1] * inv); w.y = cvtpk(o[qb][eb][2] * inv, o[qb][eb][3] * inv); *(u32x2*)(op + eb * 16) = w; }
;   }
.LBB0_373:
	v_readlane_b32 s12, v253, 4
	v_readlane_b32 s13, v253, 5
	v_exp_f32_e32 v11, v30
	v_exp_f32_e32 v12, v31
	v_exp_f32_e32 v15, v86
	v_exp_f32_e32 v16, v87
	v_exp_f32_e32 v30, v88
	v_exp_f32_e32 v31, v89
	v_exp_f32_e32 v86, v6
	v_exp_f32_e32 v87, v7
	v_exp_f32_e32 v88, v8
	v_exp_f32_e32 v89, v9
	v_readlane_b32 s14, v253, 6
	v_readlane_b32 s15, v253, 7
	v_mov_b64_e32 v[6:7], s[12:13]
	v_exp_f32_e32 v13, v84
	v_exp_f32_e32 v14, v85
	v_exp_f32_e32 v17, v72
	v_exp_f32_e32 v18, v73
	v_exp_f32_e32 v19, v74
	v_exp_f32_e32 v20, v75
	v_exp_f32_e32 v21, v76
	v_exp_f32_e32 v22, v77
	v_exp_f32_e32 v23, v78
	v_exp_f32_e32 v24, v79
	v_mov_b64_e32 v[8:9], s[14:15]
	v_exp_f32_e32 v78, v4
	v_exp_f32_e32 v79, v5
	v_cvt_pk_bf16_f32 v4, v13, v14
	v_cvt_pk_bf16_f32 v5, v15, v16
	v_cvt_pk_bf16_f32 v14, v17, v18
	v_cvt_pk_bf16_f32 v15, v19, v20
	v_cvt_pk_bf16_f32 v16, v21, v22
	v_cvt_pk_bf16_f32 v17, v23, v24
	v_exp_f32_e32 v0, v28
	v_exp_f32_e32 v10, v29
	v_mfma_f32_16x16x32_bf16 v[18:21], v[6:9], v[14:17], v[56:59]
	ds_read_b64_tr_b16 v[22:23], v157 offset:58368
	ds_read_b64_tr_b16 v[26:27], v157 offset:58400
	ds_read_b64_tr_b16 v[24:25], v157 offset:60672
	ds_read_b64_tr_b16 v[28:29], v157 offset:60704
	ds_read_b64_tr_b16 v[56:57], v157 offset:58432
	ds_read_b64_tr_b16 v[58:59], v157 offset:60736
	v_exp_f32_e32 v76, v2
	v_exp_f32_e32 v77, v3
	v_cvt_pk_bf16_f32 v2, v0, v10
	v_cvt_pk_bf16_f32 v3, v11, v12
	s_waitcnt lgkmcnt(0)
	v_mfma_f32_16x16x32_bf16 v[40:43], v[56:59], v[14:17], v[40:43]
	v_exp_f32_e32 v84, v90
	v_exp_f32_e32 v85, v91
	v_exp_f32_e32 v72, v80
	v_mfma_f32_16x16x32_bf16 v[44:47], v[56:59], v[2:5], v[44:47]
	ds_read_b64_tr_b16 v[56:57], v157 offset:58464
	ds_read_b64_tr_b16 v[58:59], v157 offset:60768
	v_exp_f32_e32 v73, v81
	v_exp_f32_e32 v74, v82
	v_exp_f32_e32 v75, v83
	v_mfma_f32_16x16x32_bf16 v[10:13], v[6:9], v[2:5], v[60:63]
	v_cvt_pk_bf16_f32 v30, v30, v31
	v_cvt_pk_bf16_f32 v31, v84, v85
	s_lshl_b32 s0, s10, 6
	v_mfma_f32_16x16x32_bf16 v[52:55], v[22:25], v[2:5], v[52:55]
	s_ashr_i32 s1, s0, 31
	s_add_i32 s9, s9, s70
	s_add_i32 s8, s8, s70
	v_mfma_f32_16x16x32_bf16 v[22:25], v[22:25], v[14:17], v[48:51]
	s_cmpk_gt_i32 s9, 0x7ff
	v_mfma_f32_16x16x32_bf16 v[48:51], v[26:29], v[2:5], v[68:71]
	v_mfma_f32_16x16x32_bf16 v[26:29], v[26:29], v[14:17], v[64:67]
	s_waitcnt lgkmcnt(0)
	v_mfma_f32_16x16x32_bf16 v[2:5], v[56:59], v[2:5], v[36:39]
	v_mfma_f32_16x16x32_bf16 v[14:17], v[56:59], v[14:17], v[32:35]
	s_nop 1
	v_cvt_pk_bf16_f32 v36, v76, v77
	v_cvt_pk_bf16_f32 v37, v78, v79
	v_cvt_pk_bf16_f32 v32, v86, v87
	v_cvt_pk_bf16_f32 v33, v88, v89
	v_cvt_pk_bf16_f32 v34, v72, v73
	v_cvt_pk_bf16_f32 v35, v74, v75
	v_mfma_f32_16x16x32_bf16 v[10:13], v[6:9], v[30:33], v[10:13]
	s_nop 0
	v_mfma_f32_16x16x32_bf16 v[6:9], v[6:9], v[34:37], v[18:21]
	s_nop 2
	ds_read_b64_tr_b16 v[18:19], v157 offset:62976
	ds_read_b64_tr_b16 v[20:21], v157 offset:65280
	s_nop 2
	v_lshl_add_u64 v[8:9], s[0:1], 1, v[130:131]
	v_div_scale_f32 v0, s[0:1], v10, v10, 1.0
	s_waitcnt lgkmcnt(0)
	v_mfma_f32_16x16x32_bf16 v[52:55], v[18:21], v[30:33], v[52:55]
	v_rcp_f32_e32 v7, v0
	s_nop 0
	v_fma_f32 v11, -v0, v7, 1.0
	v_mfma_f32_16x16x32_bf16 v[18:21], v[18:21], v[34:37], v[22:25]
	s_nop 2
	ds_read_b64_tr_b16 v[22:23], v157 offset:63008
	ds_read_b64_tr_b16 v[24:25], v157 offset:65312
	v_fmac_f32_e32 v7, v11, v7
	v_div_scale_f32 v11, vcc, 1.0, v10, 1.0
	s_waitcnt lgkmcnt(0)
	v_mfma_f32_16x16x32_bf16 v[48:51], v[22:25], v[30:33], v[48:51]
	v_mfma_f32_16x16x32_bf16 v[22:25], v[22:25], v[34:37], v[26:29]
	s_nop 2
	ds_read_b64_tr_b16 v[26:27], v157 offset:63040
	ds_read_b64_tr_b16 v[28:29], v157 offset:65344
	s_waitcnt lgkmcnt(0)
	v_mfma_f32_16x16x32_bf16 v[44:47], v[26:29], v[30:33], v[44:47]
	v_mfma_f32_16x16x32_bf16 v[26:29], v[26:29], v[34:37], v[40:43]
	ds_read_b64_tr_b16 v[38:39], v157 offset:63072
	s_nop 1
	ds_read_b64_tr_b16 v[40:41], v157 offset:65376
	s_waitcnt lgkmcnt(0)
	s_barrier
	v_mfma_f32_16x16x32_bf16 v[12:15], v[38:41], v[34:37], v[14:17]
	s_nop 2
	v_mul_f32_e32 v16, v11, v7
	v_fma_f32 v17, -v0, v16, v11
	v_fmac_f32_e32 v16, v17, v7
	v_fma_f32 v0, -v0, v16, v11
	v_div_fmas_f32 v0, v0, v7, v16
	v_mfma_f32_16x16x32_bf16 v[2:5], v[38:41], v[30:33], v[2:5]
	v_div_fixup_f32 v0, v0, v10, 1.0
	v_lshlrev_b64 v[10:11], 11, v[136:137]
	v_pk_mul_f32 v[30:31], v[0:1], v[52:53] op_sel_hi:[0,1]
	v_pk_mul_f32 v[32:33], v[0:1], v[54:55] op_sel_hi:[0,1]
	v_lshl_add_u64 v[16:17], v[8:9], 0, v[10:11]
	v_cvt_pk_bf16_f32 v30, v30, v31
	v_cvt_pk_bf16_f32 v31, v32, v33
	global_store_dwordx2 v[16:17], v[30:31], off
	v_pk_mul_f32 v[30:31], v[0:1], v[48:49] op_sel_hi:[0,1]
	v_pk_mul_f32 v[32:33], v[0:1], v[50:51] op_sel_hi:[0,1]
	v_cvt_pk_bf16_f32 v30, v30, v31
	v_cvt_pk_bf16_f32 v31, v32, v33
	v_pk_mul_f32 v[2:3], v[0:1], v[2:3] op_sel_hi:[0,1]
	v_pk_mul_f32 v[4:5], v[0:1], v[4:5] op_sel_hi:[0,1]
	global_store_dwordx2 v[16:17], v[30:31], off offset:32
	v_pk_mul_f32 v[30:31], v[0:1], v[44:45] op_sel_hi:[0,1]
	v_pk_mul_f32 v[32:33], v[0:1], v[46:47] op_sel_hi:[0,1]
	v_cvt_pk_bf16_f32 v2, v2, v3
	v_cvt_pk_bf16_f32 v3, v4, v5
	v_div_scale_f32 v0, s[0:1], v6, v6, 1.0
	global_store_dwordx2 v[16:17], v[2:3], off offset:96
	v_rcp_f32_e32 v2, v0
	v_or_b32_e32 v10, 0x8000, v10
	v_cvt_pk_bf16_f32 v30, v30, v31
	v_cvt_pk_bf16_f32 v31, v32, v33
	v_fma_f32 v3, -v0, v2, 1.0
	v_fmac_f32_e32 v2, v3, v2
	v_div_scale_f32 v3, vcc, 1.0, v6, 1.0
	v_mul_f32_e32 v4, v3, v2
	v_fma_f32 v5, -v0, v4, v3
	v_fmac_f32_e32 v4, v5, v2
	v_fma_f32 v0, -v0, v4, v3
	v_div_fmas_f32 v0, v0, v2, v4
	v_div_fixup_f32 v0, v0, v6, 1.0
	v_pk_mul_f32 v[4:5], v[0:1], v[18:19] op_sel_hi:[0,1]
	v_pk_mul_f32 v[6:7], v[0:1], v[20:21] op_sel_hi:[0,1]
	v_lshl_add_u64 v[2:3], v[8:9], 0, v[10:11]
	v_cvt_pk_bf16_f32 v4, v4, v5
	v_cvt_pk_bf16_f32 v5, v6, v7
	global_store_dwordx2 v[2:3], v[4:5], off
	v_pk_mul_f32 v[4:5], v[0:1], v[22:23] op_sel_hi:[0,1]
	v_pk_mul_f32 v[6:7], v[0:1], v[24:25] op_sel_hi:[0,1]
	v_cvt_pk_bf16_f32 v4, v4, v5
	v_cvt_pk_bf16_f32 v5, v6, v7
	global_store_dwordx2 v[2:3], v[4:5], off offset:32
	v_pk_mul_f32 v[4:5], v[0:1], v[26:27] op_sel_hi:[0,1]
	v_pk_mul_f32 v[6:7], v[0:1], v[28:29] op_sel_hi:[0,1]
	v_cvt_pk_bf16_f32 v4, v4, v5
	v_cvt_pk_bf16_f32 v5, v6, v7
	global_store_dwordx2 v[2:3], v[4:5], off offset:64
	v_pk_mul_f32 v[4:5], v[0:1], v[12:13] op_sel_hi:[0,1]
	v_pk_mul_f32 v[6:7], v[0:1], v[14:15] op_sel_hi:[0,1]
	v_cvt_pk_bf16_f32 v4, v4, v5
	v_cvt_pk_bf16_f32 v5, v6, v7
	global_store_dwordx2 v[16:17], v[30:31], off offset:64
	global_store_dwordx2 v[2:3], v[4:5], off offset:96
	s_cbranch_scc1 .LBB0_396

; #define LAS __attribute__((address_space(3)))
; __device__ __forceinline__ unsigned cvtpk(float lo, float hi) { f32x2_t v = {lo, hi}; bf16x2_t b = __builtin_convertvector(v, bf16x2_t); return __builtin_bit_cast(unsigned, b); }
; __device__ __forceinline__ f32x4 mfma16(bf16x8 a, bf16x8 b, f32x4 c) { return __builtin_amdgcn_mfma_f32_16x16x32_bf16(a, b, c, 0, 0, 0); }
; __device__ __forceinline__ u32x2 tr_rd(const LAS bf16_t* p) { return __builtin_bit_cast(u32x2, __builtin_amdgcn_ds_read_tr16_b64_v4i16((LAS v4i16_t*)p)); }
; __device__ __forceinline__ void attn_unit(LAS unsigned char* lds, const bf16_t* Q, const bf16_t* KV, const bf16_t* KR, bf16_t* MIX, size_t qrow0, size_t krow0, int ntiles, int h, const int tid) {
;     ...
;   for (int t = 0; t < ntiles; ++t) {
;     LAS unsigned char* buf = lds + (t & 1) * AT_BUF;
;     const bool more = (t + 1 < ntiles);
;     if (more) { const bf16_t* g2 = gk + (size_t)(t + 1) * 64 * 1024; rk = *(const u32x4*)g2; rv = *(const u32x4*)(g2 + 64); if (tid < 256) rr = *(const u32x4*)(gr + (size_t)(t + 1) * 64 * 32); }
;     const LAS bf16_t* Ks = (const LAS bf16_t*)buf; const LAS bf16_t* Vs = (const LAS bf16_t*)(buf + 64 * AT_KSTR * 2);
;     f32x4 s[4][2];
; #pragma unroll
;     for (int kb = 0; kb < 4; ++kb) {
;       bf16x8 kf[3];
; #pragma unroll
;       for (int ks = 0; ks < 3; ++ks) kf[ks] = *(const LAS bf16x8*)(Ks + (kb * 16 + c16) * AT_KSTR + ks * 32 + quad * 8);
;     ...
;     for (int s2 = 0; s2 < 2; ++s2) {
;       bf16x8 pf[2];
; #pragma unroll
;       for (int qb = 0; qb < 2; ++qb) { u32x4 w; w.x = cvtpk(s[2 * s2][qb][0], s[2 * s2][qb][1]); w.y = cvtpk(s[2 * s2][qb][2], s[2 * s2][qb][3]);
;         w.z = cvtpk(s[2 * s2 + 1][qb][0], s[2 * s2 + 1][qb][1]); w.w = cvtpk(s[2 * s2 + 1][qb][2], s[2 * s2 + 1][qb][3]); pf[qb] = __builtin_bit_cast(bf16x8, w);
;         lacc[qb] = mfma16(ones, pf[qb], lacc[qb]); }
;       const LAS bf16_t* vb = Vs + (32 * s2 + 4 * quad + tq) * AT_VSTR + 4 * tp;
; #pragma unroll
;       for (int eb = 0; eb < 4; ++eb) {
;         const u32x2 lo = tr_rd(vb + 16 * eb), hi = tr_rd(vb + 16 * AT_VSTR + 16 * eb);
;         const u32x4 vv = (u32x4){lo.x, lo.y, hi.x, hi.y}; const bf16x8 vf = __builtin_bit_cast(bf16x8, vv);
; #pragma unroll
;         for (int qb = 0; qb < 2; ++qb) o[qb][eb] = mfma16(vf, pf[qb], o[qb][eb]);
;       }
;     }
.LBB0_382:
	s_or_b64 exec, exec, s[4:5]
	s_and_b32 s4, s8, 7
	s_mul_i32 s5, s4, 0x84000
	s_mul_i32 s4, s4, 0x1080000
	s_lshl_b64 s[0:1], s[0:1], 1
	s_add_u32 s0, s4, s0
	v_or_b32_e32 v0, s5, v121
	s_addc_u32 s1, 0, s1
	v_pk_add_f32 v[2:3], v[2:3], 0 op_sel_hi:[1,0]
	v_lshl_add_u64 v[140:141], v[132:133], 0, v[0:1]
	v_lshl_add_u64 v[142:143], v[134:135], 0, s[0:1]
	s_mov_b32 s4, 2
	s_waitcnt vmcnt(0)
	ds_write_b128 v151, v[72:75] offset:35840
	s_waitcnt lgkmcnt(0)
	s_barrier
	v_mov_b32_e32 v198, 0x3f803f80
	v_mov_b32_e32 v199, v198
	v_mov_b32_e32 v200, v198
	v_mov_b32_e32 v201, v198
	v_xor_b32_e32 v202, 0x80000000, v2
	v_xor_b32_e32 v206, 0x80000000, v3
	v_lshlrev_b32_e32 v176, 1, v154
	v_mov_b32_e32 v203, v202
	v_mov_b32_e32 v204, v202
	v_mov_b32_e32 v205, v202
	v_mov_b32_e32 v207, v206
	v_mov_b32_e32 v208, v206
	v_mov_b32_e32 v209, v206
	s_cmp_lg_u32 s42, 0
	s_cbranch_scc1 .LBB0_384
	global_load_dwordx4 v[76:79], v[142:143], off
	global_load_dwordx4 v[72:75], v[142:143], off offset:128
	s_add_i32 s0, s4, -1
	s_mul_i32 s1, s0, 0xaaab
	s_lshr_b32 s1, s1, 17
	s_mul_i32 s1, s1, 3
	s_sub_i32 s0, s0, s1
	s_mul_i32 s1, s0, 0x5800
	s_add_i32 s5, s1, 0x5800
	s_cmp_eq_u32 s5, 0x10800
	s_cselect_b32 s5, 0, s5
	s_branch .Lat_B_mid
.Lat_B_top:
	global_load_dwordx4 v[76:79], v[142:143], off
	global_load_dwordx4 v[72:75], v[142:143], off offset:128
	s_add_i32 s0, s4, -1
	s_mul_i32 s1, s0, 0xaaab
	s_lshr_b32 s1, s1, 17
	s_mul_i32 s1, s1, 3
	s_sub_i32 s0, s0, s1
	s_mul_i32 s1, s0, 0x5800
	s_add_i32 s5, s1, 0x5800
	s_cmp_eq_u32 s5, 0x10800
	s_cselect_b32 s5, 0, s5
	s_add_i32 s0, s1, 0xffffa800
	s_cmp_lt_i32 s0, 0
	s_cselect_b32 s0, 0xb000, s0
	v_add3_u32 v139, s0, v176, v155
	ds_read_b64_tr_b16 v[170:171], v139 offset:13312
	ds_read_b64_tr_b16 v[172:173], v139 offset:15616
	ds_read_b64_tr_b16 v[210:211], v139 offset:13344
	ds_read_b64_tr_b16 v[212:213], v139 offset:15648
	ds_read_b64_tr_b16 v[214:215], v139 offset:13376
	ds_read_b64_tr_b16 v[216:217], v139 offset:15680
	ds_read_b64_tr_b16 v[218:219], v139 offset:13408
	ds_read_b64_tr_b16 v[220:221], v139 offset:15712
	ds_read_b64_tr_b16 v[240:241], v139 offset:17920
	ds_read_b64_tr_b16 v[242:243], v139 offset:20224
	ds_read_b64_tr_b16 v[244:245], v139 offset:17952
	ds_read_b64_tr_b16 v[246:247], v139 offset:20256
	ds_read_b64_tr_b16 v[158:159], v139 offset:17984
	ds_read_b64_tr_b16 v[160:161], v139 offset:20288
	s_waitcnt lgkmcnt(12)
	v_mfma_f32_16x16x32_bf16 v[52:55], v[170:173], v[80:83], v[52:55]
	v_mfma_f32_16x16x32_bf16 v[48:51], v[170:173], v[88:91], v[48:51]
	ds_read_b64_tr_b16 v[162:163], v139 offset:18016
	ds_read_b64_tr_b16 v[164:165], v139 offset:20320
	v_mfma_f32_16x16x32_bf16 v[60:63], v[198:201], v[80:83], v[60:63]
	v_mfma_f32_16x16x32_bf16 v[56:59], v[198:201], v[88:91], v[56:59]
	s_waitcnt lgkmcnt(12)
	v_mfma_f32_16x16x32_bf16 v[68:71], v[210:213], v[80:83], v[68:71]
	v_mfma_f32_16x16x32_bf16 v[64:67], v[210:213], v[88:91], v[64:67]
	s_waitcnt lgkmcnt(10)
	v_mfma_f32_16x16x32_bf16 v[44:47], v[214:217], v[80:83], v[44:47]
	v_mfma_f32_16x16x32_bf16 v[40:43], v[214:217], v[88:91], v[40:43]
	s_waitcnt lgkmcnt(8)
	v_mfma_f32_16x16x32_bf16 v[36:39], v[218:221], v[80:83], v[36:39]
	v_mfma_f32_16x16x32_bf16 v[32:35], v[218:221], v[88:91], v[32:35]
	v_mfma_f32_16x16x32_bf16 v[60:63], v[198:201], v[96:99], v[60:63]
	v_mfma_f32_16x16x32_bf16 v[56:59], v[198:201], v[104:107], v[56:59]
	s_waitcnt lgkmcnt(6)
	v_mfma_f32_16x16x32_bf16 v[52:55], v[240:243], v[96:99], v[52:55]
	v_mfma_f32_16x16x32_bf16 v[48:51], v[240:243], v[104:107], v[48:51]
	s_waitcnt lgkmcnt(4)
	v_mfma_f32_16x16x32_bf16 v[68:71], v[244:247], v[96:99], v[68:71]
	v_mfma_f32_16x16x32_bf16 v[64:67], v[244:247], v[104:107], v[64:67]
	s_waitcnt lgkmcnt(2)
	v_mfma_f32_16x16x32_bf16 v[44:47], v[158:161], v[96:99], v[44:47]
	v_mfma_f32_16x16x32_bf16 v[40:43], v[158:161], v[104:107], v[40:43]
	s_waitcnt lgkmcnt(0)
	v_mfma_f32_16x16x32_bf16 v[36:39], v[162:165], v[96:99], v[36:39]
	v_mfma_f32_16x16x32_bf16 v[32:35], v[162:165], v[104:107], v[32:35]
.Lat_B_mid:
	v_add3_u32 v0, s1, v124, v146
	ds_read_b128 v[158:161], v0
	ds_read_b128 v[162:165], v0 offset:64
	ds_read_b128 v[166:169], v0 offset:128
	ds_read_b128 v[170:173], v0 offset:3328
	ds_read_b128 v[210:213], v0 offset:3392
	ds_read_b128 v[214:217], v0 offset:3456
	ds_read_b128 v[218:221], v0 offset:6656
	ds_read_b128 v[240:243], v0 offset:6720
	ds_read_b128 v[244:247], v0 offset:6784
	s_waitcnt lgkmcnt(8)
	v_mfma_f32_16x16x32_bf16 v[80:83], v[158:161], v[4:7], v[202:205]
	v_mfma_f32_16x16x32_bf16 v[88:91], v[158:161], v[16:19], v[206:209]
	s_waitcnt lgkmcnt(7)
	v_mfma_f32_16x16x32_bf16 v[80:83], v[162:165], v[8:11], v[80:83]
	v_mfma_f32_16x16x32_bf16 v[88:91], v[162:165], v[20:23], v[88:91]
	s_waitcnt lgkmcnt(6)
	v_mfma_f32_16x16x32_bf16 v[80:83], v[166:169], v[12:15], v[80:83]
	v_mfma_f32_16x16x32_bf16 v[88:91], v[166:169], v[24:27], v[88:91]
	ds_read_b128 v[158:161], v0 offset:9984
	ds_read_b128 v[162:165], v0 offset:10048
	ds_read_b128 v[166:169], v0 offset:10112
	s_waitcnt lgkmcnt(8)
	v_mfma_f32_16x16x32_bf16 v[84:87], v[170:173], v[4:7], v[202:205]
	v_mfma_f32_16x16x32_bf16 v[92:95], v[170:173], v[16:19], v[206:209]
	s_waitcnt lgkmcnt(7)
	v_mfma_f32_16x16x32_bf16 v[84:87], v[210:213], v[8:11], v[84:87]
	v_mfma_f32_16x16x32_bf16 v[92:95], v[210:213], v[20:23], v[92:95]
	s_waitcnt lgkmcnt(6)
	v_mfma_f32_16x16x32_bf16 v[84:87], v[214:217], v[12:15], v[84:87]
	v_mfma_f32_16x16x32_bf16 v[92:95], v[214:217], v[24:27], v[92:95]
	s_waitcnt lgkmcnt(5)
	v_mfma_f32_16x16x32_bf16 v[96:99], v[218:221], v[4:7], v[202:205]
	v_mfma_f32_16x16x32_bf16 v[104:107], v[218:221], v[16:19], v[206:209]
	v_max3_f32 v174, v80, v81, v82
	s_waitcnt lgkmcnt(4)
; #define LAS __attribute__((address_space(3)))
; __device__ __forceinline__ void attn_unit(LAS unsigned char* lds, const bf16_t* Q, const bf16_t* KV, const bf16_t* KR, bf16_t* MIX, size_t qrow0, size_t krow0, int ntiles, int h, const int tid) {
;     ...
;       for (int qb = 0; qb < 2; ++qb) { const float nm = -mref[qb]; f32x4 a = (f32x4){nm, nm, nm, nm};
; #pragma unroll
;         for (int ks = 0; ks < 3; ++ks) a = mfma16(kf[ks], qf[qb][ks], a);
;         s[kb][qb] = a; }
;     }
; #pragma unroll
;     for (int qb = 0; qb < 2; ++qb) {
;       float mx = -1e30f;
; #pragma unroll
;       for (int kb = 0; kb < 4; ++kb) mx = fmaxf(fmaxf(fmaxf(s[kb][qb][0], s[kb][qb][1]), fmaxf(s[kb][qb][2], s[kb][qb][3])), mx);
;       mx = fmaxf(mx, __shfl_xor(mx, 16)); mx = fmaxf(mx, __shfl_xor(mx, 32));
;       if (t == 0 || __any(mx > 8.f)) {
;         const float delta = (t == 0) ? mx : fmaxf(mx, 0.f), alpha = (t == 0) ? 1.f : __builtin_amdgcn_exp2f(-delta);
;         mref[qb] += delta; lacc[qb] = lacc[qb] * alpha;
; #pragma unroll
;         for (int kb = 0; kb < 4; ++kb) s[kb][qb] = s[kb][qb] - delta;
; #pragma unroll
;         for (int eb = 0; eb < 4; ++eb) o[qb][eb] = o[qb][eb] * alpha;
;       }
; #pragma unroll
;       for (int kb = 0; kb < 4; ++kb)
; #pragma unroll
;         for (int r = 0; r < 4; ++r) s[kb][qb][r] = __builtin_amdgcn_exp2f(s[kb][qb][r]);
;     }
; #pragma unroll
;     for (int s2 = 0; s2 < 2; ++s2) {
;       bf16x8 pf[2];
; #pragma unroll
;       for (int qb = 0; qb < 2; ++qb) { u32x4 w; w.x = cvtpk(s[2 * s2][qb][0], s[2 * s2][qb][1]); w.y = cvtpk(s[2 * s2][qb][2], s[2 * s2][qb][3]);
;         w.z = cvtpk(s[2 * s2 + 1][qb][0], s[2 * s2 + 1][qb][1]); w.w = cvtpk(s[2 * s2 + 1][qb][2], s[2 * s2 + 1][qb][3]); pf[qb] = __builtin_bit_cast(bf16x8, w);
;         lacc[qb] = mfma16(ones, pf[qb], lacc[qb]); }
;       const LAS bf16_t* vb = Vs + (32 * s2 + 4 * quad + tq) * AT_VSTR + 4 * tp;
; #pragma unroll
;       for (int eb = 0; eb < 4; ++eb) {
;         const u32x2 lo = tr_rd(vb + 16 * eb), hi = tr_rd(vb + 16 * AT_VSTR + 16 * eb);
;         const u32x4 vv = (u32x4){lo.x, lo.y, hi.x, hi.y}; const bf16x8 vf = __builtin_bit_cast(bf16x8, vv);
; #pragma unroll
;         for (int qb = 0; qb < 2; ++qb) o[qb][eb] = mfma16(vf, pf[qb], o[qb][eb]);
;       }
;     }
;     if (more) attn_stage(lds + ((t + 1) & 1) * AT_BUF, tid, rk, rv, rr);
;     __syncthreads();
	v_mfma_f32_16x16x32_bf16 v[96:99], v[240:243], v[8:11], v[96:99]
	v_mfma_f32_16x16x32_bf16 v[104:107], v[240:243], v[20:23], v[104:107]
	v_max3_f32 v175, v88, v89, v90
	s_waitcnt lgkmcnt(3)
	v_mfma_f32_16x16x32_bf16 v[96:99], v[244:247], v[12:15], v[96:99]
	v_mfma_f32_16x16x32_bf16 v[104:107], v[244:247], v[24:27], v[104:107]
	s_waitcnt lgkmcnt(2)
	v_mfma_f32_16x16x32_bf16 v[100:103], v[158:161], v[4:7], v[202:205]
	v_mfma_f32_16x16x32_bf16 v[108:111], v[158:161], v[16:19], v[206:209]
	v_max3_f32 v174, v174, v83, v84
	s_waitcnt lgkmcnt(1)
	v_mfma_f32_16x16x32_bf16 v[100:103], v[162:165], v[8:11], v[100:103]
	v_max3_f32 v174, v174, v85, v86
	v_mfma_f32_16x16x32_bf16 v[108:111], v[162:165], v[20:23], v[108:111]
	s_waitcnt lgkmcnt(0)
	v_mfma_f32_16x16x32_bf16 v[100:103], v[166:169], v[12:15], v[100:103]
	v_max3_f32 v175, v175, v91, v92
	v_mfma_f32_16x16x32_bf16 v[108:111], v[166:169], v[24:27], v[108:111]
	v_max3_f32 v175, v175, v93, v94
	v_max3_f32 v174, v174, v87, v96
	v_max3_f32 v174, v174, v97, v98
	v_max3_f32 v175, v175, v95, v104
	v_max3_f32 v175, v175, v105, v106
	v_add3_u32 v0, s5, v148, v138
	v_add3_u32 v177, s5, v127, v138
	s_nop 0
	v_max3_f32 v174, v174, v99, v100
	v_max3_f32 v175, v175, v107, v108
	v_max3_f32 v174, v174, v101, v102
	v_max3_f32 v175, v175, v109, v110
	v_max_f32_e32 v174, v174, v103
	v_max_f32_e32 v175, v175, v111
	v_max_f32_e32 v235, v174, v175
	v_cmp_lt_f32_e32 vcc, 0x41000000, v235
	s_cbranch_vccnz .Lat_rareB
.Lat_backB:
	v_exp_f32_e32 v80, v80
	v_exp_f32_e32 v81, v81
	v_exp_f32_e32 v82, v82
	v_exp_f32_e32 v83, v83
	v_exp_f32_e32 v84, v84
	v_exp_f32_e32 v85, v85
	v_exp_f32_e32 v86, v86
	v_exp_f32_e32 v87, v87
	v_cvt_pk_bf16_f32 v80, v80, v81
	v_cvt_pk_bf16_f32 v81, v82, v83
	v_cvt_pk_bf16_f32 v82, v84, v85
	v_cvt_pk_bf16_f32 v83, v86, v87
	v_exp_f32_e32 v88, v88
	v_exp_f32_e32 v89, v89
	v_exp_f32_e32 v90, v90
	v_exp_f32_e32 v91, v91
	v_exp_f32_e32 v92, v92
	v_exp_f32_e32 v93, v93
	v_exp_f32_e32 v94, v94
	v_exp_f32_e32 v95, v95
	v_cvt_pk_bf16_f32 v88, v88, v89
	v_cvt_pk_bf16_f32 v89, v90, v91
	v_cvt_pk_bf16_f32 v90, v92, v93
	v_cvt_pk_bf16_f32 v91, v94, v95
	v_exp_f32_e32 v96, v96
	v_exp_f32_e32 v97, v97
	v_exp_f32_e32 v98, v98
	v_exp_f32_e32 v99, v99
	v_exp_f32_e32 v100, v100
	v_exp_f32_e32 v101, v101
	v_exp_f32_e32 v102, v102
	v_exp_f32_e32 v103, v103
	v_cvt_pk_bf16_f32 v96, v96, v97
	v_cvt_pk_bf16_f32 v97, v98, v99
	v_cvt_pk_bf16_f32 v98, v100, v101
	v_cvt_pk_bf16_f32 v99, v102, v103
	v_exp_f32_e32 v104, v104
	v_exp_f32_e32 v105, v105
	v_exp_f32_e32 v106, v106
	v_exp_f32_e32 v107, v107
	v_exp_f32_e32 v108, v108
	v_exp_f32_e32 v109, v109
	v_exp_f32_e32 v110, v110
	v_exp_f32_e32 v111, v111
	v_cvt_pk_bf16_f32 v104, v104, v105
	v_cvt_pk_bf16_f32 v105, v106, v107
	v_cvt_pk_bf16_f32 v106, v108, v109
	v_cvt_pk_bf16_f32 v107, v110, v111
	s_waitcnt vmcnt(0)
	ds_write_b128 v0, v[76:79]
	ds_write_b128 v177, v[72:75] offset:13312
	s_mov_b64 s[0:1], 0x1000
	s_add_i32 s4, s4, 1
	v_lshl_add_u64 v[140:141], v[140:141], 0, s[0:1]
	s_mov_b64 s[0:1], 0x20000
	v_lshl_add_u64 v[142:143], v[142:143], 0, s[0:1]
	s_cmpk_lg_i32 s4, 0x84
	s_waitcnt lgkmcnt(0)
	s_barrier
	s_cbranch_scc1 .Lat_B_top
	s_movk_i32 s0, 0x5800
	v_add3_u32 v139, s0, v176, v155
	ds_read_b64_tr_b16 v[170:171], v139 offset:13312
	ds_read_b64_tr_b16 v[172:173], v139 offset:15616
	ds_read_b64_tr_b16 v[210:211], v139 offset:13344
	ds_read_b64_tr_b16 v[212:213], v139 offset:15648
	ds_read_b64_tr_b16 v[214:215], v139 offset:13376
	ds_read_b64_tr_b16 v[216:217], v139 offset:15680
	ds_read_b64_tr_b16 v[218:219], v139 offset:13408
	ds_read_b64_tr_b16 v[220:221], v139 offset:15712
	ds_read_b64_tr_b16 v[240:241], v139 offset:17920
	ds_read_b64_tr_b16 v[242:243], v139 offset:20224
	ds_read_b64_tr_b16 v[244:245], v139 offset:17952
	ds_read_b64_tr_b16 v[246:247], v139 offset:20256
	ds_read_b64_tr_b16 v[158:159], v139 offset:17984
	ds_read_b64_tr_b16 v[160:161], v139 offset:20288
	s_waitcnt lgkmcnt(12)
	v_mfma_f32_16x16x32_bf16 v[52:55], v[170:173], v[80:83], v[52:55]
	v_mfma_f32_16x16x32_bf16 v[48:51], v[170:173], v[88:91], v[48:51]
	ds_read_b64_tr_b16 v[162:163], v139 offset:18016
	ds_read_b64_tr_b16 v[164:165], v139 offset:20320
	v_mfma_f32_16x16x32_bf16 v[60:63], v[198:201], v[80:83], v[60:63]
	v_mfma_f32_16x16x32_bf16 v[56:59], v[198:201], v[88:91], v[56:59]
	s_waitcnt lgkmcnt(12)
	v_mfma_f32_16x16x32_bf16 v[68:71], v[210:213], v[80:83], v[68:71]
	v_mfma_f32_16x16x32_bf16 v[64:67], v[210:213], v[88:91], v[64:67]
	s_waitcnt lgkmcnt(10)
	v_mfma_f32_16x16x32_bf16 v[44:47], v[214:217], v[80:83], v[44:47]
	v_mfma_f32_16x16x32_bf16 v[40:43], v[214:217], v[88:91], v[40:43]
	s_waitcnt lgkmcnt(8)
	v_mfma_f32_16x16x32_bf16 v[36:39], v[218:221], v[80:83], v[36:39]
	v_mfma_f32_16x16x32_bf16 v[32:35], v[218:221], v[88:91], v[32:35]
	v_mfma_f32_16x16x32_bf16 v[60:63], v[198:201], v[96:99], v[60:63]
	v_mfma_f32_16x16x32_bf16 v[56:59], v[198:201], v[104:107], v[56:59]
	s_waitcnt lgkmcnt(6)
	v_mfma_f32_16x16x32_bf16 v[52:55], v[240:243], v[96:99], v[52:55]
	v_mfma_f32_16x16x32_bf16 v[48:51], v[240:243], v[104:107], v[48:51]
	s_waitcnt lgkmcnt(4)
	v_mfma_f32_16x16x32_bf16 v[68:71], v[244:247], v[96:99], v[68:71]
	v_mfma_f32_16x16x32_bf16 v[64:67], v[244:247], v[104:107], v[64:67]
	s_waitcnt lgkmcnt(2)
	v_mfma_f32_16x16x32_bf16 v[44:47], v[158:161], v[96:99], v[44:47]
	v_mfma_f32_16x16x32_bf16 v[40:43], v[158:161], v[104:107], v[40:43]
	s_waitcnt lgkmcnt(0)
	v_mfma_f32_16x16x32_bf16 v[36:39], v[162:165], v[96:99], v[36:39]
	v_mfma_f32_16x16x32_bf16 v[32:35], v[162:165], v[104:107], v[32:35]
	s_branch .LBB0_392
; __device__ __forceinline__ void attn_unit(LAS unsigned char* lds, const bf16_t* Q, const bf16_t* KV, const bf16_t* KR, bf16_t* MIX, size_t qrow0, size_t krow0, int ntiles, int h, const int tid) {
;     ...
;       mx = fmaxf(mx, __shfl_xor(mx, 16)); mx = fmaxf(mx, __shfl_xor(mx, 32));
;       if (t == 0 || __any(mx > 8.f)) {
;         const float delta = (t == 0) ? mx : fmaxf(mx, 0.f), alpha = (t == 0) ? 1.f : __builtin_amdgcn_exp2f(-delta);
;         mref[qb] += delta; lacc[qb] = lacc[qb] * alpha;
; #pragma unroll
;         for (int kb = 0; kb < 4; ++kb) s[kb][qb] = s[kb][qb] - delta;
; #pragma unroll
;         for (int eb = 0; eb < 4; ++eb) o[qb][eb] = o[qb][eb] * alpha;
;       }
.Lat_rareB:
	s_waitcnt lgkmcnt(0)
	ds_bpermute_b32 v235, v152, v174
	s_waitcnt lgkmcnt(0)
	v_max_f32_e32 v174, v174, v235
	ds_bpermute_b32 v235, v153, v174
	s_waitcnt lgkmcnt(0)
	v_max_f32_e32 v174, v174, v235
	v_cmp_lt_f32_e32 vcc, 0x41000000, v174
	s_cbranch_vccz .Lat_rB1
	v_max_f32_e32 v195, 0, v174
	v_exp_f32_e64 v234, -v195
	v_add_f32_e32 v2, v2, v195
	v_sub_f32_e32 v80, v80, v195
	v_sub_f32_e32 v81, v81, v195
	v_sub_f32_e32 v82, v82, v195
	v_sub_f32_e32 v83, v83, v195
	v_sub_f32_e32 v84, v84, v195
	v_sub_f32_e32 v85, v85, v195
	v_sub_f32_e32 v86, v86, v195
	v_sub_f32_e32 v87, v87, v195
	v_sub_f32_e32 v96, v96, v195
	v_sub_f32_e32 v97, v97, v195
	v_sub_f32_e32 v98, v98, v195
	v_sub_f32_e32 v99, v99, v195
	v_sub_f32_e32 v100, v100, v195
	v_sub_f32_e32 v101, v101, v195
	v_sub_f32_e32 v102, v102, v195
	v_sub_f32_e32 v103, v103, v195
	v_pk_mul_f32 v[62:63], v[62:63], v[234:235] op_sel_hi:[1,0]
	v_pk_mul_f32 v[60:61], v[60:61], v[234:235] op_sel_hi:[1,0]
	v_pk_mul_f32 v[54:55], v[54:55], v[234:235] op_sel_hi:[1,0]
	v_pk_mul_f32 v[52:53], v[52:53], v[234:235] op_sel_hi:[1,0]
	v_pk_mul_f32 v[70:71], v[70:71], v[234:235] op_sel_hi:[1,0]
	v_pk_mul_f32 v[68:69], v[68:69], v[234:235] op_sel_hi:[1,0]
	v_pk_mul_f32 v[46:47], v[46:47], v[234:235] op_sel_hi:[1,0]
	v_pk_mul_f32 v[44:45], v[44:45], v[234:235] op_sel_hi:[1,0]
	v_pk_mul_f32 v[38:39], v[38:39], v[234:235] op_sel_hi:[1,0]
	v_pk_mul_f32 v[36:37], v[36:37], v[234:235] op_sel_hi:[1,0]
	v_xor_b32_e32 v202, 0x80000000, v2
	v_mov_b32_e32 v203, v202
	v_mov_b32_e32 v204, v202
	v_mov_b32_e32 v205, v202
.Lat_rB1:
	ds_bpermute_b32 v235, v152, v175
	s_waitcnt lgkmcnt(0)
	v_max_f32_e32 v175, v175, v235
	ds_bpermute_b32 v235, v153, v175
	s_waitcnt lgkmcnt(0)
	v_max_f32_e32 v175, v175, v235
	v_cmp_lt_f32_e32 vcc, 0x41000000, v175
	s_cbranch_vccz .Lat_rB2
	v_max_f32_e32 v195, 0, v175
	v_exp_f32_e64 v234, -v195
	v_add_f32_e32 v3, v3, v195
	v_sub_f32_e32 v88, v88, v195
	v_sub_f32_e32 v89, v89, v195
	v_sub_f32_e32 v90, v90, v195
	v_sub_f32_e32 v91, v91, v195
	v_sub_f32_e32 v92, v92, v195
	v_sub_f32_e32 v93, v93, v195
	v_sub_f32_e32 v94, v94, v195
	v_sub_f32_e32 v95, v95, v195
	v_sub_f32_e32 v104, v104, v195
	v_sub_f32_e32 v105, v105, v195
	v_sub_f32_e32 v106, v106, v195
	v_sub_f32_e32 v107, v107, v195
	v_sub_f32_e32 v108, v108, v195
	v_sub_f32_e32 v109, v109, v195
	v_sub_f32_e32 v110, v110, v195
	v_sub_f32_e32 v111, v111, v195
	v_pk_mul_f32 v[58:59], v[58:59], v[234:235] op_sel_hi:[1,0]
	v_pk_mul_f32 v[56:57], v[56:57], v[234:235] op_sel_hi:[1,0]
	v_pk_mul_f32 v[50:51], v[50:51], v[234:235] op_sel_hi:[1,0]
	v_pk_mul_f32 v[48:49], v[48:49], v[234:235] op_sel_hi:[1,0]
	v_pk_mul_f32 v[66:67], v[66:67], v[234:235] op_sel_hi:[1,0]
	v_pk_mul_f32 v[64:65], v[64:65], v[234:235] op_sel_hi:[1,0]
	v_pk_mul_f32 v[42:43], v[42:43], v[234:235] op_sel_hi:[1,0]
	v_pk_mul_f32 v[40:41], v[40:41], v[234:235] op_sel_hi:[1,0]
	v_pk_mul_f32 v[34:35], v[34:35], v[234:235] op_sel_hi:[1,0]
	v_pk_mul_f32 v[32:33], v[32:33], v[234:235] op_sel_hi:[1,0]
	v_xor_b32_e32 v206, 0x80000000, v3
	v_mov_b32_e32 v207, v206
	v_mov_b32_e32 v208, v206
	v_mov_b32_e32 v209, v206

; #define LAS __attribute__((address_space(3)))
; __device__ __forceinline__ f32x4 mfma16(bf16x8 a, bf16x8 b, f32x4 c) { return __builtin_amdgcn_mfma_f32_16x16x32_bf16(a, b, c, 0, 0, 0); }
; __device__ __forceinline__ void attn_unit(LAS unsigned char* lds, const bf16_t* Q, const bf16_t* KV, const bf16_t* KR, bf16_t* MIX, size_t qrow0, size_t krow0, int ntiles, int h, const int tid) {
;     ...
;   for (int t = 0; t < ntiles; ++t) {
;     LAS unsigned char* buf = lds + (t & 1) * AT_BUF;
;     const bool more = (t + 1 < ntiles);
;     if (more) { const bf16_t* g2 = gk + (size_t)(t + 1) * 64 * 1024; rk = *(const u32x4*)g2; rv = *(const u32x4*)(g2 + 64); if (tid < 256) rr = *(const u32x4*)(gr + (size_t)(t + 1) * 64 * 32); }
;     const LAS bf16_t* Ks = (const LAS bf16_t*)buf; const LAS bf16_t* Vs = (const LAS bf16_t*)(buf + 64 * AT_KSTR * 2);
;     f32x4 s[4][2];
; #pragma unroll
;     for (int kb = 0; kb < 4; ++kb) {
;       bf16x8 kf[3];
; #pragma unroll
;       for (int ks = 0; ks < 3; ++ks) kf[ks] = *(const LAS bf16x8*)(Ks + (kb * 16 + c16) * AT_KSTR + ks * 32 + quad * 8);
; #pragma unroll
;       for (int qb = 0; qb < 2; ++qb) { const float nm = -mref[qb]; f32x4 a = (f32x4){nm, nm, nm, nm};
; #pragma unroll
;         for (int ks = 0; ks < 3; ++ks) a = mfma16(kf[ks], qf[qb][ks], a);
;         s[kb][qb] = a; }
;     }
; #pragma unroll
;     for (int qb = 0; qb < 2; ++qb) {
;       float mx = -1e30f;
; #pragma unroll
;       for (int kb = 0; kb < 4; ++kb) mx = fmaxf(fmaxf(fmaxf(s[kb][qb][0], s[kb][qb][1]), fmaxf(s[kb][qb][2], s[kb][qb][3])), mx);
;       mx = fmaxf(mx, __shfl_xor(mx, 16)); mx = fmaxf(mx, __shfl_xor(mx, 32));
;       if (t == 0 || __any(mx > 8.f)) {
.LBB0_386:
	s_or_b64 exec, exec, s[0:1]
	s_add_i32 s0, s4, -1
	s_mul_i32 s1, s0, 0xaaab
	s_lshr_b32 s1, s1, 17
	s_mul_i32 s1, s1, 3
	s_sub_i32 s0, s0, s1
	s_mul_i32 s1, s0, 0x5800
	s_add_i32 s5, s1, 0x5800
	s_cmp_eq_u32 s5, 0x10800
	s_cselect_b32 s5, 0, s5
	v_add3_u32 v0, s1, v124, v146
	ds_read_b128 v[158:161], v0
	ds_read_b128 v[162:165], v0 offset:64
	ds_read_b128 v[166:169], v0 offset:128
	ds_read_b128 v[170:173], v0 offset:3328
	ds_read_b128 v[210:213], v0 offset:3392
	ds_read_b128 v[214:217], v0 offset:3456
	ds_read_b128 v[218:221], v0 offset:6656
	ds_read_b128 v[240:243], v0 offset:6720
	ds_read_b128 v[244:247], v0 offset:6784
	v_add3_u32 v139, s1, v176, v155
	s_waitcnt lgkmcnt(8)
	v_mfma_f32_16x16x32_bf16 v[80:83], v[158:161], v[4:7], v[202:205]
	v_mfma_f32_16x16x32_bf16 v[88:91], v[158:161], v[16:19], v[206:209]
	s_waitcnt lgkmcnt(7)
	v_mfma_f32_16x16x32_bf16 v[80:83], v[162:165], v[8:11], v[80:83]
	v_mfma_f32_16x16x32_bf16 v[88:91], v[162:165], v[20:23], v[88:91]
	s_waitcnt lgkmcnt(6)
	v_mfma_f32_16x16x32_bf16 v[80:83], v[166:169], v[12:15], v[80:83]
	v_mfma_f32_16x16x32_bf16 v[88:91], v[166:169], v[24:27], v[88:91]
	ds_read_b128 v[158:161], v0 offset:9984
	ds_read_b128 v[162:165], v0 offset:10048
	ds_read_b128 v[166:169], v0 offset:10112
	s_waitcnt lgkmcnt(8)
	v_mfma_f32_16x16x32_bf16 v[84:87], v[170:173], v[4:7], v[202:205]
	v_mfma_f32_16x16x32_bf16 v[92:95], v[170:173], v[16:19], v[206:209]
	s_waitcnt lgkmcnt(7)
	v_mfma_f32_16x16x32_bf16 v[84:87], v[210:213], v[8:11], v[84:87]
	v_mfma_f32_16x16x32_bf16 v[92:95], v[210:213], v[20:23], v[92:95]
	s_waitcnt lgkmcnt(6)
	v_mfma_f32_16x16x32_bf16 v[84:87], v[214:217], v[12:15], v[84:87]
	v_mfma_f32_16x16x32_bf16 v[92:95], v[214:217], v[24:27], v[92:95]
	ds_read_b64_tr_b16 v[170:171], v139 offset:13312
	ds_read_b64_tr_b16 v[172:173], v139 offset:15616
	ds_read_b64_tr_b16 v[210:211], v139 offset:13344
	ds_read_b64_tr_b16 v[212:213], v139 offset:15648
	ds_read_b64_tr_b16 v[214:215], v139 offset:13376
	ds_read_b64_tr_b16 v[216:217], v139 offset:15680
	s_waitcnt lgkmcnt(11)
	v_mfma_f32_16x16x32_bf16 v[96:99], v[218:221], v[4:7], v[202:205]
	v_mfma_f32_16x16x32_bf16 v[104:107], v[218:221], v[16:19], v[206:209]
	v_max3_f32 v174, v80, v81, v82
	s_waitcnt lgkmcnt(10)
	v_mfma_f32_16x16x32_bf16 v[96:99], v[240:243], v[8:11], v[96:99]
	v_mfma_f32_16x16x32_bf16 v[104:107], v[240:243], v[20:23], v[104:107]
	v_max3_f32 v175, v88, v89, v90
	s_waitcnt lgkmcnt(9)
	v_mfma_f32_16x16x32_bf16 v[96:99], v[244:247], v[12:15], v[96:99]
	v_mfma_f32_16x16x32_bf16 v[104:107], v[244:247], v[24:27], v[104:107]
	ds_read_b64_tr_b16 v[218:219], v139 offset:13408
	ds_read_b64_tr_b16 v[220:221], v139 offset:15712
	s_waitcnt lgkmcnt(10)
	v_mfma_f32_16x16x32_bf16 v[100:103], v[158:161], v[4:7], v[202:205]
	v_mfma_f32_16x16x32_bf16 v[108:111], v[158:161], v[16:19], v[206:209]
	v_max3_f32 v174, v174, v83, v84
	s_waitcnt lgkmcnt(9)
	v_mfma_f32_16x16x32_bf16 v[100:103], v[162:165], v[8:11], v[100:103]
	v_max3_f32 v174, v174, v85, v86
	v_mfma_f32_16x16x32_bf16 v[108:111], v[162:165], v[20:23], v[108:111]
	s_waitcnt lgkmcnt(8)
	v_mfma_f32_16x16x32_bf16 v[100:103], v[166:169], v[12:15], v[100:103]
	v_max3_f32 v175, v175, v91, v92
	v_mfma_f32_16x16x32_bf16 v[108:111], v[166:169], v[24:27], v[108:111]
	v_max3_f32 v175, v175, v93, v94
	v_max3_f32 v174, v174, v87, v96
	v_max3_f32 v174, v174, v97, v98
	v_max3_f32 v175, v175, v95, v104
	v_max3_f32 v175, v175, v105, v106
	ds_read_b64_tr_b16 v[240:241], v139 offset:17920
	ds_read_b64_tr_b16 v[242:243], v139 offset:20224
	ds_read_b64_tr_b16 v[244:245], v139 offset:17952
	ds_read_b64_tr_b16 v[246:247], v139 offset:20256
	ds_read_b64_tr_b16 v[158:159], v139 offset:17984
	ds_read_b64_tr_b16 v[160:161], v139 offset:20288
	v_max3_f32 v174, v174, v99, v100
	v_max3_f32 v175, v175, v107, v108
	v_max3_f32 v174, v174, v101, v102
	v_max3_f32 v175, v175, v109, v110
	v_max_f32_e32 v174, v174, v103
	v_max_f32_e32 v175, v175, v111
	v_max_f32_e32 v0, v174, v175
	v_cmp_lt_f32_e32 vcc, 0x41000000, v0
	s_cbranch_vccnz .Lat_rareA

; #define LAS __attribute__((address_space(3)))
; __device__ __forceinline__ f32x4 mfma16(bf16x8 a, bf16x8 b, f32x4 c) { return __builtin_amdgcn_mfma_f32_16x16x32_bf16(a, b, c, 0, 0, 0); }
; __device__ __forceinline__ void attn_unit(LAS unsigned char* lds, const bf16_t* Q, const bf16_t* KV, const bf16_t* KR, bf16_t* MIX, size_t qrow0, size_t krow0, int ntiles, int h, const int tid) {
;     ...
;     const LAS bf16_t* Ks = (const LAS bf16_t*)buf; const LAS bf16_t* Vs = (const LAS bf16_t*)(buf + 64 * AT_KSTR * 2);
;     f32x4 s[4][2];
; #pragma unroll
;     for (int kb = 0; kb < 4; ++kb) {
;       bf16x8 kf[3];
; #pragma unroll
;       for (int ks = 0; ks < 3; ++ks) kf[ks] = *(const LAS bf16x8*)(Ks + (kb * 16 + c16) * AT_KSTR + ks * 32 + quad * 8);
; #pragma unroll
;       for (int qb = 0; qb < 2; ++qb) { const float nm = -mref[qb]; f32x4 a = (f32x4){nm, nm, nm, nm};
; #pragma unroll
;         for (int ks = 0; ks < 3; ++ks) a = mfma16(kf[ks], qf[qb][ks], a);
;         s[kb][qb] = a; }
;     }
; #pragma unroll
;     for (int qb = 0; qb < 2; ++qb) {
;       float mx = -1e30f;
; #pragma unroll
;       for (int kb = 0; kb < 4; ++kb) mx = fmaxf(fmaxf(fmaxf(s[kb][qb][0], s[kb][qb][1]), fmaxf(s[kb][qb][2], s[kb][qb][3])), mx);
;       mx = fmaxf(mx, __shfl_xor(mx, 16)); mx = fmaxf(mx, __shfl_xor(mx, 32));
;       if (t == 0 || __any(mx > 8.f)) {
;         const float delta = (t == 0) ? mx : fmaxf(mx, 0.f), alpha = (t == 0) ? 1.f : __builtin_amdgcn_exp2f(-delta);
;         mref[qb] += delta; lacc[qb] = lacc[qb] * alpha;
; #pragma unroll
;         for (int kb = 0; kb < 4; ++kb) s[kb][qb] = s[kb][qb] - delta;
; #pragma unroll
;         for (int eb = 0; eb < 4; ++eb) o[qb][eb] = o[qb][eb] * alpha;
;       }
.LBB0_392:
	ds_read_b128 v[72:75], v156 offset:45056
	ds_read_b128 v[76:79], v156 offset:45120
	ds_read_b128 v[80:83], v156 offset:45184
	v_xor_b32_e32 v92, 0x80000000, v2
	v_xor_b32_e32 v96, 0x80000000, v3
	v_mov_b32_e32 v93, v92
	v_mov_b32_e32 v94, v92
	v_mov_b32_e32 v95, v92
	v_mov_b32_e32 v97, v96
	v_mov_b32_e32 v98, v96
	v_mov_b32_e32 v99, v96
	s_waitcnt lgkmcnt(2)
	v_mfma_f32_16x16x32_bf16 v[28:31], v[72:75], v[4:7], v[92:95]
	s_mov_b32 s0, 0x41000000
	v_mfma_f32_16x16x32_bf16 v[72:75], v[72:75], v[16:19], v[96:99]
	s_waitcnt lgkmcnt(1)
	v_mfma_f32_16x16x32_bf16 v[28:31], v[76:79], v[8:11], v[28:31]
	v_mfma_f32_16x16x32_bf16 v[72:75], v[76:79], v[20:23], v[72:75]
	s_waitcnt lgkmcnt(0)
	v_mfma_f32_16x16x32_bf16 v[28:31], v[80:83], v[12:15], v[28:31]
	v_mfma_f32_16x16x32_bf16 v[72:75], v[80:83], v[24:27], v[72:75]
	ds_read_b128 v[76:79], v156 offset:48384
	ds_read_b128 v[80:83], v156 offset:48448
	ds_read_b128 v[88:91], v156 offset:48512
	s_nop 3
	v_max_f32_e32 v0, v29, v29
	s_waitcnt lgkmcnt(2)
	v_mfma_f32_16x16x32_bf16 v[84:87], v[76:79], v[4:7], v[92:95]
	v_mfma_f32_16x16x32_bf16 v[76:79], v[76:79], v[16:19], v[96:99]
	s_waitcnt lgkmcnt(1)
	v_mfma_f32_16x16x32_bf16 v[84:87], v[80:83], v[8:11], v[84:87]
	v_mfma_f32_16x16x32_bf16 v[76:79], v[80:83], v[20:23], v[76:79]
	ds_read_b128 v[80:83], v156 offset:51712
	ds_read_b128 v[100:103], v156 offset:51776
	ds_read_b128 v[104:107], v156 offset:51840
	s_waitcnt lgkmcnt(3)
	v_mfma_f32_16x16x32_bf16 v[84:87], v[88:91], v[12:15], v[84:87]
	v_mfma_f32_16x16x32_bf16 v[76:79], v[88:91], v[24:27], v[76:79]
	s_waitcnt lgkmcnt(2)
	v_mfma_f32_16x16x32_bf16 v[88:91], v[80:83], v[4:7], v[92:95]
	v_mfma_f32_16x16x32_bf16 v[80:83], v[80:83], v[16:19], v[96:99]
	s_waitcnt lgkmcnt(1)
	v_mfma_f32_16x16x32_bf16 v[88:91], v[100:103], v[8:11], v[88:91]
	v_mfma_f32_16x16x32_bf16 v[80:83], v[100:103], v[20:23], v[80:83]
	s_waitcnt lgkmcnt(0)
	v_mfma_f32_16x16x32_bf16 v[88:91], v[104:107], v[12:15], v[88:91]
	v_mfma_f32_16x16x32_bf16 v[80:83], v[104:107], v[24:27], v[80:83]
	ds_read_b128 v[100:103], v156 offset:55040
	ds_read_b128 v[104:107], v156 offset:55104
	ds_read_b128 v[108:111], v156 offset:55168
	s_waitcnt lgkmcnt(2)
	v_mfma_f32_16x16x32_bf16 v[2:5], v[100:103], v[4:7], v[92:95]
	s_waitcnt lgkmcnt(1)
	v_mfma_f32_16x16x32_bf16 v[2:5], v[104:107], v[8:11], v[2:5]
	v_max_f32_e32 v10, v28, v28
	v_max_f32_e32 v0, v10, v0
	v_max_f32_e32 v10, v31, v31
	v_max_f32_e32 v11, v30, v30
	v_max_f32_e32 v10, v11, v10
	v_max3_f32 v0, v0, v10, s3
	v_max_f32_e32 v10, v85, v85
	v_max_f32_e32 v11, v84, v84
	s_waitcnt lgkmcnt(0)
	v_mfma_f32_16x16x32_bf16 v[6:9], v[108:111], v[12:15], v[2:5]
	v_max_f32_e32 v10, v11, v10
	v_max_f32_e32 v11, v87, v87
	v_max_f32_e32 v12, v86, v86
	v_max_f32_e32 v11, v12, v11
	v_max3_f32 v0, v10, v11, v0
	v_max_f32_e32 v10, v89, v89
	v_max_f32_e32 v11, v88, v88
	v_max_f32_e32 v10, v11, v10
	v_max_f32_e32 v11, v91, v91
	v_max_f32_e32 v12, v90, v90
	v_max_f32_e32 v11, v12, v11
	v_max3_f32 v0, v10, v11, v0
	v_max_f32_e32 v10, v7, v7
	v_max_f32_e32 v11, v6, v6
	v_max_f32_e32 v10, v11, v10
	v_max_f32_e32 v11, v9, v9
	v_max_f32_e32 v12, v8, v8
	v_max_f32_e32 v11, v12, v11
	v_max3_f32 v0, v10, v11, v0
	ds_bpermute_b32 v10, v152, v0
	v_mfma_f32_16x16x32_bf16 v[2:5], v[100:103], v[16:19], v[96:99]
	s_waitcnt lgkmcnt(0)
	v_max_f32_e32 v10, v10, v10
	v_max_f32_e32 v0, v0, v10
	v_mfma_f32_16x16x32_bf16 v[2:5], v[104:107], v[20:23], v[2:5]
	ds_bpermute_b32 v10, v153, v0
	s_waitcnt lgkmcnt(0)
	v_max_f32_e32 v10, v10, v10
	v_mfma_f32_16x16x32_bf16 v[2:5], v[108:111], v[24:27], v[2:5]
	v_max_f32_e32 v0, v0, v10
	v_cmp_lt_f32_e32 vcc, s0, v0
	s_cbranch_vccz .LBB0_394
	v_max_f32_e32 v0, v0, v0
	v_max_f32_e32 v10, 0, v0
	v_exp_f32_e64 v0, -v10
	v_sub_f32_e32 v28, v28, v10
	v_sub_f32_e32 v29, v29, v10
	v_sub_f32_e32 v30, v30, v10
	v_pk_mul_f32 v[62:63], v[62:63], v[0:1] op_sel_hi:[1,0]
	v_pk_mul_f32 v[60:61], v[60:61], v[0:1] op_sel_hi:[1,0]
	v_sub_f32_e32 v31, v31, v10
	v_sub_f32_e32 v84, v84, v10
	v_sub_f32_e32 v85, v85, v10
	v_sub_f32_e32 v86, v86, v10
	v_sub_f32_e32 v87, v87, v10
	v_sub_f32_e32 v88, v88, v10
	v_sub_f32_e32 v89, v89, v10
	v_sub_f32_e32 v90, v90, v10
	v_sub_f32_e32 v91, v91, v10
	v_sub_f32_e32 v6, v6, v10
	v_sub_f32_e32 v7, v7, v10
	v_sub_f32_e32 v8, v8, v10
	v_sub_f32_e32 v9, v9, v10
	v_pk_mul_f32 v[54:55], v[54:55], v[0:1] op_sel_hi:[1,0]
	v_pk_mul_f32 v[52:53], v[52:53], v[0:1] op_sel_hi:[1,0]
	v_pk_mul_f32 v[70:71], v[70:71], v[0:1] op_sel_hi:[1,0]
	v_pk_mul_f32 v[68:69], v[68:69], v[0:1] op_sel_hi:[1,0]
	v_pk_mul_f32 v[46:47], v[46:47], v[0:1] op_sel_hi:[1,0]
	v_pk_mul_f32 v[44:45], v[44:45], v[0:1] op_sel_hi:[1,0]
	v_pk_mul_f32 v[38:39], v[38:39], v[0:1] op_sel_hi:[1,0]
	v_pk_mul_f32 v[36:37], v[36:37], v[0:1] op_sel_hi:[1,0]
